# v55 + row passes 1/2 deal rows by gw = 256*wave + block instead of 8*block + wave: the 512 ninth rows and the ctx rows spread over all workgroups instead of 64
# baseline (speedup 1.0000x reference)
; #define ws (opq(P.ws))
; __device__ __forceinline__ void row_pass(const Params& P, int l, int mode, LAS float* pl) {
;     const int tid_ = opaque_tid(), lane = tid_ & 63; const int NGW = gridDim.x * NWAVES, gw = blockIdx.x * NWAVES + __builtin_amdgcn_readfirstlane(tid_ >> 6);
;     unsigned char* ws = P.ws;
;     float* xres = (float*)(ws + WS_XRES); const bf16_t* Y = (const bf16_t*)(ws + WS_Y); bf16_t* H = (bf16_t*)(ws + WS_H);
;     const float* mod = (const float*)(ws + WS_MOD); float* ssb = (float*)(ws + WS_SS); const float* y32 = (const float*)(ws + WS_Y32);
;     const bool lastl = (l == DEPTH - 1);
;     const bool latent_only = lastl && mode != 0;
;     const int nrows = latent_only ? BATCH * SEQ : MROWS;
;     const int gidx = (mode == 1) ? 2 : 5;
;     const int ml = (mode == 2) ? l + 1 : l;
;     const int shi = (mode == 1) ? 3 : 0;
;     const bool make_h = !(lastl && mode == 2);
;     const bool from_in = (mode == 0) || (mode == 1 && l == 0);
;     const float* lg = (mode == 1) ? P.ln1_g + l * DM : P.ln2_g + l * DM;
;     const float* lb = (mode == 1) ? P.ln1_b + l * DM : P.ln2_b + l * DM;
;     { const int t_ = opaque_tid();
;       for (int i = t_; i < 3 * DM; i += NTHREADS) { const int mvi = i >> 10, c = i & 1023;
;           if (mode != 0) pl[i] = mod[(size_t)(l * 3 + mvi) * NMOD + gidx * DM + c];
;           if (make_h) { pl[5120 + i] = mod[(size_t)(ml * 3 + mvi) * NMOD + shi * DM + c]; pl[8192 + i] = mod[(size_t)(ml * 3 + mvi) * NMOD + (shi + 1) * DM + c] + 1.0f; } }
;       if (mode != 0) for (int i = t_; i < DM; i += NTHREADS) { pl[3072 + i] = lg[i]; pl[4096 + i] = lb[i]; }
;       asm volatile("s_waitcnt lgkmcnt(0)" ::: "memory"); __syncthreads(); }
;     f32x4 nx[2][4]; u32x2 ny[2][4];
;     ...
;     if (gw < nrows) RP_ISSUE(gw);
;     for (int i0 = gw; i0 < nrows; i0 += 2 * NGW) {
;         f32x4 v[2][4], yv[2][4]; u32x2 yr[2][4]; int row[2], mv[2]; bool ok[2]; float* dst[2];
; #pragma unroll
;         for (int r = 0; r < 2; ++r)
; #pragma unroll
;             for (int j = 0; j < 4; ++j) { v[r][j] = nx[r][j]; yr[r][j] = ny[r][j]; }
;         if (i0 + 2 * NGW < nrows) RP_ISSUE(i0 + 2 * NGW);
;         __builtin_amdgcn_sched_barrier(0);
; #pragma unroll
;         for (int r = 0; r < 2; ++r) {
;             const int i = i0 + r * NGW; ok[r] = i < nrows; const int ii = ok[r] ? i : i0;
.LBB0_965:
	s_or_b64 exec, exec, s[6:7]
	s_ashr_i32 s0, s2, 6
	v_readlane_b32 s1, v253, 52
	s_lshr_b32 s1, s1, 3
	s_lshl_b32 s0, s0, 8
	s_add_i32 s22, s0, s1
	v_readlane_b32 s0, v252, 9
	s_cmp_lg_u32 s0, 3
	s_cselect_b64 s[36:37], -1, 0
	s_cmp_eq_u32 s0, 3
	v_readlane_b32 s1, v252, 10
	s_cselect_b64 s[38:39], -1, 0
	s_mov_b32 s2, s0
	s_and_b64 s[0:1], s[38:39], exec
	s_movk_i32 s0, 0x4200
	s_cselect_b32 s68, 0x4000, s0
	s_cmp_lg_u32 s2, 0
	s_waitcnt lgkmcnt(0)
	s_cselect_b64 s[6:7], -1, 0
	s_cmp_lt_i32 s22, s68
	v_and_b32_e32 v4, 63, v6
	s_cselect_b64 s[0:1], -1, 0
	s_cmp_ge_i32 s22, s68
	s_waitcnt lgkmcnt(0)
	s_barrier
	s_cbranch_scc1 .LBB0_994
	s_mov_b64 s[4:5], -1
	s_and_b64 vcc, exec, s[36:37]
	s_cbranch_vccz .LBB0_968
	s_add_i32 s2, s22, 0x600
	s_mul_hi_i32 s3, s2, 0x3e0f83e1
	s_lshr_b32 s4, s3, 31
	s_ashr_i32 s3, s3, 12
	s_add_i32 s3, s3, s4
	s_mulk_i32 s3, 0x4200
	s_sub_i32 s2, s2, s3
	s_sext_i32_i16 s3, s2
	s_mulk_i32 s3, 0x3e1
	s_lshr_b32 s4, s3, 31
	s_ashr_i32 s3, s3, 23
	s_add_i32 s8, s3, s4
	s_mul_i32 s3, s8, 0x2100
	s_sub_i32 s2, s2, s3
	s_sext_i32_i16 s10, s2
	s_mov_b64 s[4:5], 0

; #define ws (opq(P.ws))
; __device__ __forceinline__ void row_pass(const Params& P, int l, int mode, LAS float* pl) {
;     const int tid_ = opaque_tid(), lane = tid_ & 63; const int NGW = gridDim.x * NWAVES, gw = blockIdx.x * NWAVES + __builtin_amdgcn_readfirstlane(tid_ >> 6);
;     unsigned char* ws = P.ws;
;     float* xres = (float*)(ws + WS_XRES); const bf16_t* Y = (const bf16_t*)(ws + WS_Y); bf16_t* H = (bf16_t*)(ws + WS_H);
;     const float* mod = (const float*)(ws + WS_MOD); float* ssb = (float*)(ws + WS_SS); const float* y32 = (const float*)(ws + WS_Y32);
;     const bool lastl = (l == DEPTH - 1);
;     const bool latent_only = lastl && mode != 0;
;     const int nrows = latent_only ? BATCH * SEQ : MROWS;
;     const int gidx = (mode == 1) ? 2 : 5;
;     const int ml = (mode == 2) ? l + 1 : l;
;     const int shi = (mode == 1) ? 3 : 0;
;     const bool make_h = !(lastl && mode == 2);
;     const bool from_in = (mode == 0) || (mode == 1 && l == 0);
;     const float* lg = (mode == 1) ? P.ln1_g + l * DM : P.ln2_g + l * DM;
;     const float* lb = (mode == 1) ? P.ln1_b + l * DM : P.ln2_b + l * DM;
;     { const int t_ = opaque_tid();
;       for (int i = t_; i < 3 * DM; i += NTHREADS) { const int mvi = i >> 10, c = i & 1023;
;           if (mode != 0) pl[i] = mod[(size_t)(l * 3 + mvi) * NMOD + gidx * DM + c];
;           if (make_h) { pl[5120 + i] = mod[(size_t)(ml * 3 + mvi) * NMOD + shi * DM + c]; pl[8192 + i] = mod[(size_t)(ml * 3 + mvi) * NMOD + (shi + 1) * DM + c] + 1.0f; } }
;       if (mode != 0) for (int i = t_; i < DM; i += NTHREADS) { pl[3072 + i] = lg[i]; pl[4096 + i] = lb[i]; }
;       asm volatile("s_waitcnt lgkmcnt(0)" ::: "memory"); __syncthreads(); }
;     f32x4 nx[2][4]; u32x2 ny[2][4];
;     ...
;     if (gw < nrows) RP_ISSUE(gw);
;     for (int i0 = gw; i0 < nrows; i0 += 2 * NGW) {
;         f32x4 v[2][4], yv[2][4]; u32x2 yr[2][4]; int row[2], mv[2]; bool ok[2]; float* dst[2];
; #pragma unroll
;         for (int r = 0; r < 2; ++r)
; #pragma unroll
;             for (int j = 0; j < 4; ++j) { v[r][j] = nx[r][j]; yr[r][j] = ny[r][j]; }
;         if (i0 + 2 * NGW < nrows) RP_ISSUE(i0 + 2 * NGW);
;         __builtin_amdgcn_sched_barrier(0);
; #pragma unroll
;         for (int r = 0; r < 2; ++r) {
;             const int i = i0 + r * NGW; ok[r] = i < nrows; const int ii = ok[r] ? i : i0;
.LBB0_1260:
	s_or_b64 exec, exec, s[8:9]
	s_ashr_i32 s0, s2, 6
	v_readlane_b32 s1, v253, 52
	s_lshr_b32 s1, s1, 3
	s_lshl_b32 s0, s0, 8
	s_add_i32 s2, s0, s1
	s_waitcnt lgkmcnt(0)
	s_cmp_lt_i32 s2, s68
	v_and_b32_e32 v4, 63, v6
	s_cselect_b64 s[0:1], -1, 0
	s_cmp_ge_i32 s2, s68
	s_waitcnt lgkmcnt(0)
	s_barrier
	s_cbranch_scc1 .LBB0_1273
	s_mov_b64 s[6:7], -1
	s_and_b64 vcc, exec, s[36:37]
	s_cbranch_vccz .LBB0_1263
	s_add_i32 s3, s2, 0x600
	s_mul_hi_i32 s6, s3, 0x3e0f83e1
	s_lshr_b32 s7, s6, 31
	s_ashr_i32 s6, s6, 12
	s_add_i32 s6, s6, s7
	s_mulk_i32 s6, 0x4200
	s_sub_i32 s3, s3, s6
	s_sext_i32_i16 s6, s3
	s_mulk_i32 s6, 0x3e1
	s_lshr_b32 s7, s6, 31
	s_ashr_i32 s6, s6, 23
	s_add_i32 s8, s6, s7
	s_mul_i32 s6, s8, 0x2100
	s_sub_i32 s3, s3, s6
	s_sext_i32_i16 s3, s3
	s_mov_b64 s[6:7], 0
